# GEMM tiles: first K-loop iteration peeled; its first MFMA into each accumulator takes the constant-zero C operand, the 128 accumulator clears per tile are gone
# speedup vs baseline: 1.0029x; 1.0029x over previous
; #define PG8_STAGE(bufoff, gbase, voff) do { _Pragma("unroll") for (int _i = 0; _i < 2; ++_i) \
;         __builtin_amdgcn_global_load_lds((const unsigned*)((const char*)(gbase) + (voff)[_i]), (PG8_LAS unsigned*)(lds + (bufoff) + ldsw + _i * 8192), 16, 0, 0); } while (0)
; #define PG8_LDA(dst, b, h) do { _Pragma("unroll") for (int m = 0; m < 4; ++m) _Pragma("unroll") for (int k = 0; k < 2; ++k) dst[m][k] = *(const PG8_LAS bf16x8*)(lds + PG8_SA(b, h) + aoff + m * 2048 + k * 1024); } while (0)
; #define PG8_LDB(dst, b, h) do { _Pragma("unroll") for (int n = 0; n < 2; ++n) _Pragma("unroll") for (int k = 0; k < 2; ++k) dst[n][k] = *(const PG8_LAS bf16x8*)(lds + PG8_SB(b, h) + boff + n * 2048 + k * 1024); } while (0)
; #define PG8_WAIT_V(n) asm volatile("s_waitcnt vmcnt(" #n ")" ::: "memory")
; #define PG8_WAIT_L(n) asm volatile("s_waitcnt lgkmcnt(" #n ")" ::: "memory")
; #define PG8_BAR __builtin_amdgcn_s_barrier()
; #define PG8_SCHED __builtin_amdgcn_sched_barrier(0)
; template <class Epi, class Sched, bool ALIGN_EPI = false, bool SP2 = false>
; __device__ __forceinline__ void gemm_phase(PG8_LAS unsigned char* lds, const Gemm g, const Sched& S, const Epi& E) {
;     ...
;         const bool has_next = S.next(ui + 1, nxt);
;         const char* nA = has_next ? (const char*)g.A + (size_t)nxt.pm * tstep : cA; const char* nB = has_next ? (const char*)g.Bt + (size_t)nxt.pn * tstep : cB;
;         for (int t = 0; t < nt; t += 2) {
;             const bool last = (t == nt - 2);
;             const char* a1 = cA + (size_t)(t + 1) * kstep;
;             const char* a2 = last ? nA : cA + (size_t)(t + 2) * kstep; const char* b2 = last ? nB : cB + (size_t)(t + 2) * kstep;
;             const char* a3 = a2 + kstep; const char* b3 = b2 + kstep;
;             if (last && has_next) S.a_ready(nxt);
;             if constexpr (SP2) {
;             PG8_LDB(B0, 0, 0); PG8_LDB(B1, 0, 1); PG8_SCHED; PG8_LDA(At, 0, 0); PG8_STAGE(PG8_SA(1, 1), a1 + hstep, voffA);
;             PG8_WAIT_V(8); PG8_WAIT_L(0); PG8_BAR; PG8_MMA(0, 0, At, B0); PG8_MMA(0, 1, At, B1); PG8_BAR; PG8_SCHED;
;             PG8_LDA(At, 0, 1); PG8_STAGE(PG8_SB(0, 0), b2, voffB); PG8_STAGE(PG8_SB(0, 1), b2 + hstep, voffB); PG8_STAGE(PG8_SA(0, 0), a2, voffA);
;             PG8_WAIT_V(8); PG8_WAIT_L(0); PG8_BAR; PG8_MMA(1, 0, At, B0); PG8_MMA(1, 1, At, B1); PG8_BAR; PG8_SCHED;
.Lstg_done:
	s_ashr_i32 s27, s26, 31
	s_lshl_b64 s[12:13], s[26:27], 20
	s_add_u32 s94, s18, s12
	s_addc_u32 s95, s19, s13
	s_and_b64 s[12:13], s[46:47], exec
	s_cselect_b32 s27, s95, s69
	s_cselect_b32 s86, s94, s68
	s_ashr_i32 s17, s16, 31
	s_lshl_b64 s[12:13], s[16:17], 20
	v_readlane_b32 s14, v254, 38
	v_readlane_b32 s15, v254, 39
	s_add_u32 s14, s14, s12
	s_addc_u32 s15, s15, s13
	s_and_b64 s[12:13], s[46:47], exec
	s_cselect_b32 s17, s15, s11
	s_cselect_b32 s88, s14, s10
	s_add_u32 vcc_lo, s68, 0x80080
	s_addc_u32 vcc_hi, s69, 0
	s_add_u32 s21, s10, 0x100
	s_addc_u32 s12, s11, 0
	s_mov_b32 s13, -2
	v_add_u32_e32 v218, 0x10000, v194
	s_add_u32 s10, vcc_lo, 0xfff80080
	s_addc_u32 s11, vcc_hi, -1
	s_add_i32 s84, 0, 0x10000
	s_cmp_eq_u32 s13, 28
	s_cselect_b32 s69, s27, s11
	s_cselect_b32 s68, s86, s10
	s_cselect_b32 s11, s17, s12
	s_cselect_b32 s10, s88, s21
	s_add_i32 s93, 0, 0x14000
	ds_read_b128 v[114:117], v218
	ds_read_b128 v[118:121], v218 offset:1024
	ds_read_b128 v[130:133], v218 offset:2048
	ds_read_b128 v[138:141], v218 offset:3072
	ds_read_b128 v[146:149], v218 offset:16384
	ds_read_b128 v[156:159], v218 offset:17408
	ds_read_b128 v[160:163], v218 offset:18432
	ds_read_b128 v[164:167], v218 offset:19456
	s_add_i32 m0, s2, 0xc000
	ds_read_b128 v[168:171], v199
	ds_read_b128 v[172:175], v199 offset:1024
	ds_read_b128 v[176:179], v199 offset:2048
	ds_read_b128 v[180:183], v199 offset:3072
	ds_read_b128 v[184:187], v199 offset:4096
	ds_read_b128 v[188:191], v199 offset:5120
	ds_read_b128 v[200:203], v199 offset:6144
	ds_read_b128 v[204:207], v199 offset:7168
	global_load_lds_dwordx4 v152, vcc
	s_add_i32 m0, s2, 0xe000
	s_nop 0
	global_load_lds_dwordx4 v154, vcc
	s_waitcnt vmcnt(8)
	s_waitcnt lgkmcnt(0)
	s_setprio 1
	s_barrier
	v_mfma_f32_16x16x32_bf16 v[142:145], v[114:117], v[168:171], 0
	v_mfma_f32_16x16x32_bf16 v[62:65], v[130:133], v[168:171], 0
	v_mfma_f32_16x16x32_bf16 v[122:125], v[114:117], v[176:179], 0
	v_mfma_f32_16x16x32_bf16 v[50:53], v[130:133], v[176:179], 0
	v_mfma_f32_16x16x32_bf16 v[106:109], v[114:117], v[184:187], 0
	v_mfma_f32_16x16x32_bf16 v[42:45], v[130:133], v[184:187], 0
	v_mfma_f32_16x16x32_bf16 v[98:101], v[114:117], v[200:203], 0
	v_mfma_f32_16x16x32_bf16 v[34:37], v[130:133], v[200:203], 0
	v_mfma_f32_16x16x32_bf16 v[142:145], v[118:121], v[172:175], v[142:145]
	v_mfma_f32_16x16x32_bf16 v[62:65], v[138:141], v[172:175], v[62:65]
	v_mfma_f32_16x16x32_bf16 v[122:125], v[118:121], v[180:183], v[122:125]
	v_mfma_f32_16x16x32_bf16 v[50:53], v[138:141], v[180:183], v[50:53]
	v_mfma_f32_16x16x32_bf16 v[106:109], v[118:121], v[188:191], v[106:109]
	v_mfma_f32_16x16x32_bf16 v[42:45], v[138:141], v[188:191], v[42:45]
	v_mfma_f32_16x16x32_bf16 v[98:101], v[118:121], v[204:207], v[98:101]
	v_mfma_f32_16x16x32_bf16 v[34:37], v[138:141], v[204:207], v[34:37]
	v_mfma_f32_16x16x32_bf16 v[134:137], v[146:149], v[168:171], 0
	v_mfma_f32_16x16x32_bf16 v[58:61], v[160:163], v[168:171], 0
	v_mfma_f32_16x16x32_bf16 v[126:129], v[146:149], v[176:179], 0
	v_mfma_f32_16x16x32_bf16 v[54:57], v[160:163], v[176:179], 0
	v_mfma_f32_16x16x32_bf16 v[110:113], v[146:149], v[184:187], 0
	v_mfma_f32_16x16x32_bf16 v[46:49], v[160:163], v[184:187], 0
	v_mfma_f32_16x16x32_bf16 v[102:105], v[146:149], v[200:203], 0
	v_mfma_f32_16x16x32_bf16 v[38:41], v[160:163], v[200:203], 0
	v_mfma_f32_16x16x32_bf16 v[134:137], v[156:159], v[172:175], v[134:137]
	v_mfma_f32_16x16x32_bf16 v[58:61], v[164:167], v[172:175], v[58:61]
	v_mfma_f32_16x16x32_bf16 v[126:129], v[156:159], v[180:183], v[126:129]
	v_mfma_f32_16x16x32_bf16 v[54:57], v[164:167], v[180:183], v[54:57]
	v_mfma_f32_16x16x32_bf16 v[110:113], v[156:159], v[188:191], v[110:113]
	v_mfma_f32_16x16x32_bf16 v[46:49], v[164:167], v[188:191], v[46:49]
	v_mfma_f32_16x16x32_bf16 v[102:105], v[156:159], v[204:207], v[102:105]
	v_mfma_f32_16x16x32_bf16 v[38:41], v[164:167], v[204:207], v[38:41]
	s_barrier
	s_setprio 0
	s_add_i32 s84, s84, s1
	s_add_u32 s100, s10, 0x80
	s_addc_u32 s101, s11, 0
	s_mov_b32 m0, s84
	ds_read_b128 v[168:171], v199 offset:16384
	ds_read_b128 v[172:175], v199 offset:17408
	ds_read_b128 v[176:179], v199 offset:18432
	ds_read_b128 v[180:183], v199 offset:19456
	ds_read_b128 v[184:187], v199 offset:20480
	ds_read_b128 v[188:191], v199 offset:21504
	ds_read_b128 v[200:203], v199 offset:22528
	ds_read_b128 v[204:207], v199 offset:23552
	global_load_lds_dwordx4 v0, s[10:11]
	s_add_i32 m0, s84, 0x2000
	s_add_u32 s84, s10, 0x80000
	s_addc_u32 s85, s11, 0
	s_add_i32 s93, s93, s1
	global_load_lds_dwordx4 v150, s[10:11]
	s_mov_b32 m0, s93
	s_add_u32 s98, s68, 0x80
	s_addc_u32 s99, s69, 0
	global_load_lds_dwordx4 v0, s[84:85]
	s_add_i32 m0, s93, 0x2000
	s_nop 0
	global_load_lds_dwordx4 v150, s[84:85]
	s_mov_b32 m0, s2
	s_nop 0
	global_load_lds_dwordx4 v0, s[68:69]
	s_mov_b32 m0, s4
	s_nop 0
	global_load_lds_dwordx4 v150, s[68:69]
	s_waitcnt vmcnt(8)
	s_waitcnt lgkmcnt(0)
	s_setprio 1
	s_barrier
; #define PG8_STAGE(bufoff, gbase, voff) do { _Pragma("unroll") for (int _i = 0; _i < 2; ++_i) \
;         __builtin_amdgcn_global_load_lds((const unsigned*)((const char*)(gbase) + (voff)[_i]), (PG8_LAS unsigned*)(lds + (bufoff) + ldsw + _i * 8192), 16, 0, 0); } while (0)
; #define PG8_LDA(dst, b, h) do { _Pragma("unroll") for (int m = 0; m < 4; ++m) _Pragma("unroll") for (int k = 0; k < 2; ++k) dst[m][k] = *(const PG8_LAS bf16x8*)(lds + PG8_SA(b, h) + aoff + m * 2048 + k * 1024); } while (0)
; #define PG8_LDB(dst, b, h) do { _Pragma("unroll") for (int n = 0; n < 2; ++n) _Pragma("unroll") for (int k = 0; k < 2; ++k) dst[n][k] = *(const PG8_LAS bf16x8*)(lds + PG8_SB(b, h) + boff + n * 2048 + k * 1024); } while (0)
; #define PG8_MMA(ai, bj, At, Bt) do { __builtin_amdgcn_s_setprio(1); _Pragma("unroll") for (int m = 0; m < 4; ++m) _Pragma("unroll") for (int n = 0; n < 2; ++n) _Pragma("unroll") for (int k = 0; k < 2; ++k) \
;         acc[ai][bj][m][n] = __builtin_amdgcn_mfma_f32_16x16x32_bf16(Bt[n][k], At[m][k], acc[ai][bj][m][n], 0, 0, 0); __builtin_amdgcn_s_setprio(0); } while (0)
; #define PG8_WAIT_V(n) asm volatile("s_waitcnt vmcnt(" #n ")" ::: "memory")
; #define PG8_WAIT_L(n) asm volatile("s_waitcnt lgkmcnt(" #n ")" ::: "memory")
; #define PG8_BAR __builtin_amdgcn_s_barrier()
; #define PG8_SCHED __builtin_amdgcn_sched_barrier(0)
; template <class Epi, class Sched, bool ALIGN_EPI = false, bool SP2 = false>
; __device__ __forceinline__ void gemm_phase(PG8_LAS unsigned char* lds, const Gemm g, const Sched& S, const Epi& E) {
;     ...
;             PG8_WAIT_V(8); PG8_WAIT_L(0); PG8_BAR; PG8_MMA(1, 0, At, B0); PG8_MMA(1, 1, At, B1); PG8_BAR; PG8_SCHED;
;             PG8_LDB(B0, 1, 0); PG8_LDB(B1, 1, 1); PG8_SCHED; PG8_LDA(At, 1, 0); PG8_STAGE(PG8_SA(0, 1), a2 + hstep, voffA);
;             PG8_WAIT_V(8); PG8_WAIT_L(0); PG8_BAR; PG8_MMA(0, 0, At, B0); PG8_MMA(0, 1, At, B1); PG8_BAR; PG8_SCHED;
	v_mfma_f32_16x16x32_bf16 v[94:97], v[114:117], v[168:171], 0
	v_mfma_f32_16x16x32_bf16 v[30:33], v[130:133], v[168:171], 0
	v_mfma_f32_16x16x32_bf16 v[82:85], v[114:117], v[176:179], 0
	v_mfma_f32_16x16x32_bf16 v[18:21], v[130:133], v[176:179], 0
	v_mfma_f32_16x16x32_bf16 v[74:77], v[114:117], v[184:187], 0
	v_mfma_f32_16x16x32_bf16 v[10:13], v[130:133], v[184:187], 0
	v_mfma_f32_16x16x32_bf16 v[66:69], v[114:117], v[200:203], 0
	v_mfma_f32_16x16x32_bf16 v[2:5], v[130:133], v[200:203], 0
	v_mfma_f32_16x16x32_bf16 v[94:97], v[118:121], v[172:175], v[94:97]
	v_mfma_f32_16x16x32_bf16 v[30:33], v[138:141], v[172:175], v[30:33]
	v_mfma_f32_16x16x32_bf16 v[82:85], v[118:121], v[180:183], v[82:85]
	v_mfma_f32_16x16x32_bf16 v[18:21], v[138:141], v[180:183], v[18:21]
	v_mfma_f32_16x16x32_bf16 v[74:77], v[118:121], v[188:191], v[74:77]
	v_mfma_f32_16x16x32_bf16 v[10:13], v[138:141], v[188:191], v[10:13]
	v_mfma_f32_16x16x32_bf16 v[66:69], v[118:121], v[204:207], v[66:69]
	v_mfma_f32_16x16x32_bf16 v[2:5], v[138:141], v[204:207], v[2:5]
	v_mfma_f32_16x16x32_bf16 v[90:93], v[146:149], v[168:171], 0
	v_mfma_f32_16x16x32_bf16 v[26:29], v[160:163], v[168:171], 0
	v_mfma_f32_16x16x32_bf16 v[86:89], v[146:149], v[176:179], 0
	v_mfma_f32_16x16x32_bf16 v[22:25], v[160:163], v[176:179], 0
	v_mfma_f32_16x16x32_bf16 v[78:81], v[146:149], v[184:187], 0
	v_mfma_f32_16x16x32_bf16 v[14:17], v[160:163], v[184:187], 0
	v_mfma_f32_16x16x32_bf16 v[70:73], v[146:149], v[200:203], 0
	v_mfma_f32_16x16x32_bf16 v[6:9], v[160:163], v[200:203], 0
	v_mfma_f32_16x16x32_bf16 v[90:93], v[156:159], v[172:175], v[90:93]
	v_mfma_f32_16x16x32_bf16 v[26:29], v[164:167], v[172:175], v[26:29]
	v_mfma_f32_16x16x32_bf16 v[86:89], v[156:159], v[180:183], v[86:89]
	v_mfma_f32_16x16x32_bf16 v[22:25], v[164:167], v[180:183], v[22:25]
	v_mfma_f32_16x16x32_bf16 v[78:81], v[156:159], v[188:191], v[78:81]
	v_mfma_f32_16x16x32_bf16 v[14:17], v[164:167], v[188:191], v[14:17]
	v_mfma_f32_16x16x32_bf16 v[70:73], v[156:159], v[204:207], v[70:73]
	v_mfma_f32_16x16x32_bf16 v[6:9], v[164:167], v[204:207], v[6:9]
	s_barrier
	s_setprio 0
	s_add_i32 s84, 0, 0x18000
	s_add_i32 s85, 0, 0x1c000
	ds_read_b128 v[114:117], v218 offset:32768
	ds_read_b128 v[118:121], v218 offset:33792
	ds_read_b128 v[130:133], v218 offset:34816
	ds_read_b128 v[138:141], v218 offset:35840
	ds_read_b128 v[146:149], v218 offset:49152
	ds_read_b128 v[156:159], v218 offset:50176
	ds_read_b128 v[160:163], v218 offset:51200
	ds_read_b128 v[164:167], v218 offset:52224
	s_add_u32 s68, s68, 0x80000
	s_addc_u32 s69, s69, 0
	s_mov_b32 m0, s5
	ds_read_b128 v[168:171], v199 offset:32768
	ds_read_b128 v[172:175], v199 offset:33792
	ds_read_b128 v[176:179], v199 offset:34816
	ds_read_b128 v[180:183], v199 offset:35840
	ds_read_b128 v[184:187], v199 offset:36864
	ds_read_b128 v[188:191], v199 offset:37888
	ds_read_b128 v[200:203], v199 offset:38912
	ds_read_b128 v[204:207], v199 offset:39936
	global_load_lds_dwordx4 v0, s[68:69]
	s_mov_b32 m0, s6
	s_nop 0
	global_load_lds_dwordx4 v150, s[68:69]
	s_waitcnt vmcnt(8)
	s_waitcnt lgkmcnt(0)
	s_setprio 1
	s_barrier
	v_mfma_f32_16x16x32_bf16 v[142:145], v[114:117], v[168:171], v[142:145]
	v_mfma_f32_16x16x32_bf16 v[62:65], v[130:133], v[168:171], v[62:65]
	v_mfma_f32_16x16x32_bf16 v[122:125], v[114:117], v[176:179], v[122:125]
	v_mfma_f32_16x16x32_bf16 v[50:53], v[130:133], v[176:179], v[50:53]
	v_mfma_f32_16x16x32_bf16 v[106:109], v[114:117], v[184:187], v[106:109]
	v_mfma_f32_16x16x32_bf16 v[42:45], v[130:133], v[184:187], v[42:45]
	v_mfma_f32_16x16x32_bf16 v[98:101], v[114:117], v[200:203], v[98:101]
	v_mfma_f32_16x16x32_bf16 v[34:37], v[130:133], v[200:203], v[34:37]
	v_mfma_f32_16x16x32_bf16 v[142:145], v[118:121], v[172:175], v[142:145]
	v_mfma_f32_16x16x32_bf16 v[62:65], v[138:141], v[172:175], v[62:65]
	v_mfma_f32_16x16x32_bf16 v[122:125], v[118:121], v[180:183], v[122:125]
	v_mfma_f32_16x16x32_bf16 v[50:53], v[138:141], v[180:183], v[50:53]
	v_mfma_f32_16x16x32_bf16 v[106:109], v[118:121], v[188:191], v[106:109]
	v_mfma_f32_16x16x32_bf16 v[42:45], v[138:141], v[188:191], v[42:45]
	v_mfma_f32_16x16x32_bf16 v[98:101], v[118:121], v[204:207], v[98:101]
	v_mfma_f32_16x16x32_bf16 v[34:37], v[138:141], v[204:207], v[34:37]
	v_mfma_f32_16x16x32_bf16 v[134:137], v[146:149], v[168:171], v[134:137]
	v_mfma_f32_16x16x32_bf16 v[58:61], v[160:163], v[168:171], v[58:61]
	v_mfma_f32_16x16x32_bf16 v[126:129], v[146:149], v[176:179], v[126:129]
	v_mfma_f32_16x16x32_bf16 v[54:57], v[160:163], v[176:179], v[54:57]
	v_mfma_f32_16x16x32_bf16 v[110:113], v[146:149], v[184:187], v[110:113]
	v_mfma_f32_16x16x32_bf16 v[46:49], v[160:163], v[184:187], v[46:49]
	v_mfma_f32_16x16x32_bf16 v[102:105], v[146:149], v[200:203], v[102:105]
	v_mfma_f32_16x16x32_bf16 v[38:41], v[160:163], v[200:203], v[38:41]
	v_mfma_f32_16x16x32_bf16 v[134:137], v[156:159], v[172:175], v[134:137]
	v_mfma_f32_16x16x32_bf16 v[58:61], v[164:167], v[172:175], v[58:61]
	v_mfma_f32_16x16x32_bf16 v[126:129], v[156:159], v[180:183], v[126:129]
	v_mfma_f32_16x16x32_bf16 v[54:57], v[164:167], v[180:183], v[54:57]
	v_mfma_f32_16x16x32_bf16 v[110:113], v[156:159], v[188:191], v[110:113]
	v_mfma_f32_16x16x32_bf16 v[46:49], v[164:167], v[188:191], v[46:49]
	v_mfma_f32_16x16x32_bf16 v[102:105], v[156:159], v[204:207], v[102:105]
	v_mfma_f32_16x16x32_bf16 v[38:41], v[164:167], v[204:207], v[38:41]
	s_barrier
; #define PG8_STAGE(bufoff, gbase, voff) do { _Pragma("unroll") for (int _i = 0; _i < 2; ++_i) \
;         __builtin_amdgcn_global_load_lds((const unsigned*)((const char*)(gbase) + (voff)[_i]), (PG8_LAS unsigned*)(lds + (bufoff) + ldsw + _i * 8192), 16, 0, 0); } while (0)
; #define PG8_LDA(dst, b, h) do { _Pragma("unroll") for (int m = 0; m < 4; ++m) _Pragma("unroll") for (int k = 0; k < 2; ++k) dst[m][k] = *(const PG8_LAS bf16x8*)(lds + PG8_SA(b, h) + aoff + m * 2048 + k * 1024); } while (0)
; #define PG8_MMA(ai, bj, At, Bt) do { __builtin_amdgcn_s_setprio(1); _Pragma("unroll") for (int m = 0; m < 4; ++m) _Pragma("unroll") for (int n = 0; n < 2; ++n) _Pragma("unroll") for (int k = 0; k < 2; ++k) \
;         acc[ai][bj][m][n] = __builtin_amdgcn_mfma_f32_16x16x32_bf16(Bt[n][k], At[m][k], acc[ai][bj][m][n], 0, 0, 0); __builtin_amdgcn_s_setprio(0); } while (0)
; #define PG8_WAIT_V(n) asm volatile("s_waitcnt vmcnt(" #n ")" ::: "memory")
; #define PG8_WAIT_L(n) asm volatile("s_waitcnt lgkmcnt(" #n ")" ::: "memory")
; #define PG8_BAR __builtin_amdgcn_s_barrier()
; #define PG8_SCHED __builtin_amdgcn_sched_barrier(0)
; template <class Epi, class Sched, bool ALIGN_EPI = false, bool SP2 = false>
; __device__ __forceinline__ void gemm_phase(PG8_LAS unsigned char* lds, const Gemm g, const Sched& S, const Epi& E) {
;     ...
;         for (int t = 0; t < nt; t += 2) {
;     ...
;             PG8_LDA(At, 1, 1); PG8_STAGE(PG8_SB(1, 0), b3, voffB); PG8_STAGE(PG8_SB(1, 1), b3 + hstep, voffB); PG8_STAGE(PG8_SA(1, 0), a3, voffA);
;             PG8_WAIT_V(8); PG8_WAIT_L(0); PG8_BAR; PG8_MMA(1, 0, At, B0); PG8_MMA(1, 1, At, B1); PG8_BAR; PG8_SCHED;
	s_setprio 0
	s_add_i32 s68, s84, s1
	s_mov_b32 m0, s68
	ds_read_b128 v[168:171], v199 offset:49152
	ds_read_b128 v[172:175], v199 offset:50176
	ds_read_b128 v[176:179], v199 offset:51200
	ds_read_b128 v[180:183], v199 offset:52224
	ds_read_b128 v[184:187], v199 offset:53248
	ds_read_b128 v[188:191], v199 offset:54272
	ds_read_b128 v[200:203], v199 offset:55296
	ds_read_b128 v[204:207], v199 offset:56320
	global_load_lds_dwordx4 v0, s[100:101]
	s_add_i32 m0, s68, 0x2000
	s_add_i32 s68, s85, s1
	global_load_lds_dwordx4 v150, s[100:101]
	s_add_u32 s10, s10, 0x80080
	s_addc_u32 s11, s11, 0
	s_mov_b32 m0, s68
	s_nop 0
	global_load_lds_dwordx4 v0, s[10:11]
	s_add_i32 m0, s68, 0x2000
	s_nop 0
	global_load_lds_dwordx4 v150, s[10:11]
	s_mov_b32 m0, s7
	s_nop 0
	global_load_lds_dwordx4 v0, s[98:99]
	s_mov_b32 m0, s30
	s_nop 0
	global_load_lds_dwordx4 v150, s[98:99]
	s_waitcnt vmcnt(8)
	s_waitcnt lgkmcnt(0)
	s_setprio 1
	s_barrier
	v_mfma_f32_16x16x32_bf16 v[94:97], v[114:117], v[168:171], v[94:97]
	v_mfma_f32_16x16x32_bf16 v[30:33], v[130:133], v[168:171], v[30:33]
	v_mfma_f32_16x16x32_bf16 v[82:85], v[114:117], v[176:179], v[82:85]
	v_mfma_f32_16x16x32_bf16 v[18:21], v[130:133], v[176:179], v[18:21]
	v_mfma_f32_16x16x32_bf16 v[74:77], v[114:117], v[184:187], v[74:77]
	v_mfma_f32_16x16x32_bf16 v[10:13], v[130:133], v[184:187], v[10:13]
	v_mfma_f32_16x16x32_bf16 v[66:69], v[114:117], v[200:203], v[66:69]
	v_mfma_f32_16x16x32_bf16 v[2:5], v[130:133], v[200:203], v[2:5]
	v_mfma_f32_16x16x32_bf16 v[94:97], v[118:121], v[172:175], v[94:97]
	v_mfma_f32_16x16x32_bf16 v[30:33], v[138:141], v[172:175], v[30:33]
	v_mfma_f32_16x16x32_bf16 v[82:85], v[118:121], v[180:183], v[82:85]
	v_mfma_f32_16x16x32_bf16 v[18:21], v[138:141], v[180:183], v[18:21]
	v_mfma_f32_16x16x32_bf16 v[74:77], v[118:121], v[188:191], v[74:77]
	v_mfma_f32_16x16x32_bf16 v[10:13], v[138:141], v[188:191], v[10:13]
	v_mfma_f32_16x16x32_bf16 v[66:69], v[118:121], v[204:207], v[66:69]
	v_mfma_f32_16x16x32_bf16 v[2:5], v[138:141], v[204:207], v[2:5]
	v_mfma_f32_16x16x32_bf16 v[90:93], v[146:149], v[168:171], v[90:93]
	v_mfma_f32_16x16x32_bf16 v[26:29], v[160:163], v[168:171], v[26:29]
	v_mfma_f32_16x16x32_bf16 v[86:89], v[146:149], v[176:179], v[86:89]
	v_mfma_f32_16x16x32_bf16 v[22:25], v[160:163], v[176:179], v[22:25]
	v_mfma_f32_16x16x32_bf16 v[78:81], v[146:149], v[184:187], v[78:81]
	v_mfma_f32_16x16x32_bf16 v[14:17], v[160:163], v[184:187], v[14:17]
	v_mfma_f32_16x16x32_bf16 v[70:73], v[146:149], v[200:203], v[70:73]
	v_mfma_f32_16x16x32_bf16 v[6:9], v[160:163], v[200:203], v[6:9]
	v_mfma_f32_16x16x32_bf16 v[90:93], v[156:159], v[172:175], v[90:93]
	v_mfma_f32_16x16x32_bf16 v[26:29], v[164:167], v[172:175], v[26:29]
	v_mfma_f32_16x16x32_bf16 v[86:89], v[156:159], v[180:183], v[86:89]
	v_mfma_f32_16x16x32_bf16 v[22:25], v[164:167], v[180:183], v[22:25]
	v_mfma_f32_16x16x32_bf16 v[78:81], v[156:159], v[188:191], v[78:81]
	v_mfma_f32_16x16x32_bf16 v[14:17], v[164:167], v[188:191], v[14:17]
	v_mfma_f32_16x16x32_bf16 v[70:73], v[156:159], v[204:207], v[70:73]
	v_mfma_f32_16x16x32_bf16 v[6:9], v[164:167], v[204:207], v[6:9]
	s_barrier
	s_setprio 0
	s_add_i32 s13, s13, 2
	s_add_u32 vcc_lo, vcc_lo, 0x100
	s_addc_u32 vcc_hi, vcc_hi, 0
	s_add_u32 s21, s21, 0x100
	s_addc_u32 s12, s12, 0

; #define PG8_STAGE(bufoff, gbase, voff) do { _Pragma("unroll") for (int _i = 0; _i < 2; ++_i) \
;         __builtin_amdgcn_global_load_lds((const unsigned*)((const char*)(gbase) + (voff)[_i]), (PG8_LAS unsigned*)(lds + (bufoff) + ldsw + _i * 8192), 16, 0, 0); } while (0)
; #define PG8_LDA(dst, b, h) do { _Pragma("unroll") for (int m = 0; m < 4; ++m) _Pragma("unroll") for (int k = 0; k < 2; ++k) dst[m][k] = *(const PG8_LAS bf16x8*)(lds + PG8_SA(b, h) + aoff + m * 2048 + k * 1024); } while (0)
; #define PG8_WAIT_V(n) asm volatile("s_waitcnt vmcnt(" #n ")" ::: "memory")
; #define PG8_WAIT_L(n) asm volatile("s_waitcnt lgkmcnt(" #n ")" ::: "memory")
; template <class Epi, class Sched, bool ALIGN_EPI = false, bool SP2 = false>
; __device__ __forceinline__ void gemm_phase(PG8_LAS unsigned char* lds, const Gemm g, const Sched& S, const Epi& E) {
;     ...
;         const bool has_next = S.next(ui + 1, nxt);
;         const char* nA = has_next ? (const char*)g.A + (size_t)nxt.pm * tstep : cA; const char* nB = has_next ? (const char*)g.Bt + (size_t)nxt.pn * tstep : cB;
;         for (int t = 0; t < nt; t += 2) {
;             const bool last = (t == nt - 2);
;             const char* a1 = cA + (size_t)(t + 1) * kstep;
;             const char* a2 = last ? nA : cA + (size_t)(t + 2) * kstep; const char* b2 = last ? nB : cB + (size_t)(t + 2) * kstep;
;             const char* a3 = a2 + kstep; const char* b3 = b2 + kstep;
;             if (last && has_next) S.a_ready(nxt);
;             if constexpr (SP2) {
;             PG8_LDB(B0, 0, 0); PG8_LDB(B1, 0, 1); PG8_SCHED; PG8_LDA(At, 0, 0); PG8_STAGE(PG8_SA(1, 1), a1 + hstep, voffA);
;             PG8_WAIT_V(8); PG8_WAIT_L(0); PG8_BAR; PG8_MMA(0, 0, At, B0); PG8_MMA(0, 1, At, B1); PG8_BAR; PG8_SCHED;
;             PG8_LDA(At, 0, 1); PG8_STAGE(PG8_SB(0, 0), b2, voffB); PG8_STAGE(PG8_SB(0, 1), b2 + hstep, voffB); PG8_STAGE(PG8_SA(0, 0), a2, voffA);
;             PG8_WAIT_V(8); PG8_WAIT_L(0); PG8_BAR; PG8_MMA(1, 0, At, B0); PG8_MMA(1, 1, At, B1); PG8_BAR; PG8_SCHED;
;     ...
; #pragma unroll
;         for (int a = 0; a < 2; ++a)
; #pragma unroll
;             for (int b = 0; b < 2; ++b)
; #pragma unroll
;                 for (int m = 0; m < 4; ++m)
; #pragma unroll
;                     for (int n = 0; n < 2; ++n) acc[a][b][m][n] = (f32x4){0.f, 0.f, 0.f, 0.f};
;         cur = nxt; cA = nA; cB = nB; ++ui;
.LBB0_222:
	s_add_u32 s8, s8, 0x80
	s_addc_u32 s9, s9, 0
	s_add_u32 s12, s10, 0x100
	s_addc_u32 s13, s11, 0
	s_mov_b32 s10, 0
	s_waitcnt lgkmcnt(0)
	v_add_u32_e32 v218, 0x10000, v145
	s_add_i32 s14, s10, 2
	s_add_u32 s15, s8, 0x80
	s_addc_u32 s11, s9, 0
	s_add_i32 s64, 0, 0x10000
	s_cmp_eq_u32 s57, s10
	s_cselect_b32 s11, s51, s11
	s_cselect_b32 s10, s50, s15
	s_cselect_b32 s45, s53, s13
	s_cselect_b32 s44, s52, s12
	s_add_i32 s15, 0, 0x14000
	ds_read_b128 v[140:143], v218
	ds_read_b128 v[148:151], v218 offset:1024
	ds_read_b128 v[152:155], v218 offset:2048
	ds_read_b128 v[156:159], v218 offset:3072
	ds_read_b128 v[160:163], v218 offset:16384
	ds_read_b128 v[164:167], v218 offset:17408
	ds_read_b128 v[168:171], v218 offset:18432
	ds_read_b128 v[172:175], v218 offset:19456
	s_add_i32 m0, s21, 0xc000
	ds_read_b128 v[176:179], v147
	ds_read_b128 v[180:183], v147 offset:1024
	ds_read_b128 v[184:187], v147 offset:2048
	ds_read_b128 v[188:191], v147 offset:3072
	ds_read_b128 v[192:195], v147 offset:4096
	ds_read_b128 v[196:199], v147 offset:5120
	ds_read_b128 v[200:203], v147 offset:6144
	ds_read_b128 v[204:207], v147 offset:7168
	global_load_lds_dwordx4 v136, s[8:9]
	s_add_i32 m0, s21, 0xe000
	s_nop 0
	global_load_lds_dwordx4 v138, s[8:9]
	s_waitcnt vmcnt(8)
	s_waitcnt lgkmcnt(0)
	s_setprio 1
	s_barrier
	v_mfma_f32_16x16x32_bf16 v[126:129], v[140:143], v[176:179], 0
	v_mfma_f32_16x16x32_bf16 v[122:125], v[152:155], v[176:179], 0
	v_mfma_f32_16x16x32_bf16 v[110:113], v[140:143], v[184:187], 0
	v_mfma_f32_16x16x32_bf16 v[106:109], v[152:155], v[184:187], 0
	v_mfma_f32_16x16x32_bf16 v[94:97], v[140:143], v[192:195], 0
	v_mfma_f32_16x16x32_bf16 v[90:93], v[152:155], v[192:195], 0
	v_mfma_f32_16x16x32_bf16 v[78:81], v[140:143], v[200:203], 0
	v_mfma_f32_16x16x32_bf16 v[74:77], v[152:155], v[200:203], 0
	v_mfma_f32_16x16x32_bf16 v[126:129], v[148:151], v[180:183], v[126:129]
	v_mfma_f32_16x16x32_bf16 v[122:125], v[156:159], v[180:183], v[122:125]
	v_mfma_f32_16x16x32_bf16 v[110:113], v[148:151], v[188:191], v[110:113]
	v_mfma_f32_16x16x32_bf16 v[106:109], v[156:159], v[188:191], v[106:109]
	v_mfma_f32_16x16x32_bf16 v[94:97], v[148:151], v[196:199], v[94:97]
	v_mfma_f32_16x16x32_bf16 v[90:93], v[156:159], v[196:199], v[90:93]
	v_mfma_f32_16x16x32_bf16 v[78:81], v[148:151], v[204:207], v[78:81]
	v_mfma_f32_16x16x32_bf16 v[74:77], v[156:159], v[204:207], v[74:77]
	v_mfma_f32_16x16x32_bf16 v[118:121], v[160:163], v[176:179], 0
	v_mfma_f32_16x16x32_bf16 v[114:117], v[168:171], v[176:179], 0
	v_mfma_f32_16x16x32_bf16 v[102:105], v[160:163], v[184:187], 0
	v_mfma_f32_16x16x32_bf16 v[98:101], v[168:171], v[184:187], 0
	v_mfma_f32_16x16x32_bf16 v[86:89], v[160:163], v[192:195], 0
	v_mfma_f32_16x16x32_bf16 v[82:85], v[168:171], v[192:195], 0
	v_mfma_f32_16x16x32_bf16 v[70:73], v[160:163], v[200:203], 0
	v_mfma_f32_16x16x32_bf16 v[66:69], v[168:171], v[200:203], 0
	v_mfma_f32_16x16x32_bf16 v[118:121], v[164:167], v[180:183], v[118:121]
	v_mfma_f32_16x16x32_bf16 v[114:117], v[172:175], v[180:183], v[114:117]
	v_mfma_f32_16x16x32_bf16 v[102:105], v[164:167], v[188:191], v[102:105]
	v_mfma_f32_16x16x32_bf16 v[98:101], v[172:175], v[188:191], v[98:101]
	v_mfma_f32_16x16x32_bf16 v[86:89], v[164:167], v[196:199], v[86:89]
	v_mfma_f32_16x16x32_bf16 v[82:85], v[172:175], v[196:199], v[82:85]
	v_mfma_f32_16x16x32_bf16 v[70:73], v[164:167], v[204:207], v[70:73]
	v_mfma_f32_16x16x32_bf16 v[66:69], v[172:175], v[204:207], v[66:69]
	s_barrier
	s_setprio 0
	s_add_i32 s64, s64, s7
	s_add_u32 s98, s44, 0x80
	s_addc_u32 s99, s45, 0
	s_mov_b32 m0, s64
	ds_read_b128 v[176:179], v147 offset:16384
	ds_read_b128 v[180:183], v147 offset:17408
	ds_read_b128 v[184:187], v147 offset:18432
	ds_read_b128 v[188:191], v147 offset:19456
	ds_read_b128 v[192:195], v147 offset:20480
	ds_read_b128 v[196:199], v147 offset:21504
	ds_read_b128 v[200:203], v147 offset:22528
	ds_read_b128 v[204:207], v147 offset:23552
	global_load_lds_dwordx4 v0, s[44:45]
	s_add_i32 m0, s64, 0x2000
	s_add_i32 s15, s15, s7
	global_load_lds_dwordx4 v134, s[44:45]
	s_add_u32 s44, s44, s30
	s_addc_u32 s45, s45, 0
	s_add_u32 s100, s44, 0x80
	s_addc_u32 s101, s45, 0
	s_mov_b32 m0, s15
	s_add_u32 vcc_lo, s10, 0x80
	s_addc_u32 vcc_hi, s11, 0
	global_load_lds_dwordx4 v0, s[44:45]
	s_add_i32 m0, s15, 0x2000
	s_nop 0
	global_load_lds_dwordx4 v134, s[44:45]
	s_mov_b32 m0, s21
	s_nop 0
	global_load_lds_dwordx4 v130, s[10:11]
	s_mov_b32 m0, s26
	s_nop 0
	global_load_lds_dwordx4 v132, s[10:11]
	s_waitcnt vmcnt(8)
	s_waitcnt lgkmcnt(0)
	s_setprio 1
	s_barrier
	v_mfma_f32_16x16x32_bf16 v[62:65], v[140:143], v[176:179], 0
	v_mfma_f32_16x16x32_bf16 v[58:61], v[152:155], v[176:179], 0
	v_mfma_f32_16x16x32_bf16 v[46:49], v[140:143], v[184:187], 0
	v_mfma_f32_16x16x32_bf16 v[42:45], v[152:155], v[184:187], 0
	v_mfma_f32_16x16x32_bf16 v[30:33], v[140:143], v[192:195], 0
	v_mfma_f32_16x16x32_bf16 v[26:29], v[152:155], v[192:195], 0
	v_mfma_f32_16x16x32_bf16 v[14:17], v[140:143], v[200:203], 0
	v_mfma_f32_16x16x32_bf16 v[10:13], v[152:155], v[200:203], 0
	v_mfma_f32_16x16x32_bf16 v[62:65], v[148:151], v[180:183], v[62:65]
	v_mfma_f32_16x16x32_bf16 v[58:61], v[156:159], v[180:183], v[58:61]
	v_mfma_f32_16x16x32_bf16 v[46:49], v[148:151], v[188:191], v[46:49]
	v_mfma_f32_16x16x32_bf16 v[42:45], v[156:159], v[188:191], v[42:45]
	v_mfma_f32_16x16x32_bf16 v[30:33], v[148:151], v[196:199], v[30:33]
	v_mfma_f32_16x16x32_bf16 v[26:29], v[156:159], v[196:199], v[26:29]
	v_mfma_f32_16x16x32_bf16 v[14:17], v[148:151], v[204:207], v[14:17]
	v_mfma_f32_16x16x32_bf16 v[10:13], v[156:159], v[204:207], v[10:13]
	v_mfma_f32_16x16x32_bf16 v[54:57], v[160:163], v[176:179], 0
	v_mfma_f32_16x16x32_bf16 v[50:53], v[168:171], v[176:179], 0
	v_mfma_f32_16x16x32_bf16 v[38:41], v[160:163], v[184:187], 0
	v_mfma_f32_16x16x32_bf16 v[34:37], v[168:171], v[184:187], 0
	v_mfma_f32_16x16x32_bf16 v[22:25], v[160:163], v[192:195], 0
	v_mfma_f32_16x16x32_bf16 v[18:21], v[168:171], v[192:195], 0
	v_mfma_f32_16x16x32_bf16 v[6:9], v[160:163], v[200:203], 0
	v_mfma_f32_16x16x32_bf16 v[2:5], v[168:171], v[200:203], 0
	v_mfma_f32_16x16x32_bf16 v[54:57], v[164:167], v[180:183], v[54:57]
	v_mfma_f32_16x16x32_bf16 v[50:53], v[172:175], v[180:183], v[50:53]
	v_mfma_f32_16x16x32_bf16 v[38:41], v[164:167], v[188:191], v[38:41]
	v_mfma_f32_16x16x32_bf16 v[34:37], v[172:175], v[188:191], v[34:37]
	v_mfma_f32_16x16x32_bf16 v[22:25], v[164:167], v[196:199], v[22:25]
	v_mfma_f32_16x16x32_bf16 v[18:21], v[172:175], v[196:199], v[18:21]
	v_mfma_f32_16x16x32_bf16 v[6:9], v[164:167], v[204:207], v[6:9]
	v_mfma_f32_16x16x32_bf16 v[2:5], v[172:175], v[204:207], v[2:5]
	s_barrier
; #define PG8_STAGE(bufoff, gbase, voff) do { _Pragma("unroll") for (int _i = 0; _i < 2; ++_i) \
;         __builtin_amdgcn_global_load_lds((const unsigned*)((const char*)(gbase) + (voff)[_i]), (PG8_LAS unsigned*)(lds + (bufoff) + ldsw + _i * 8192), 16, 0, 0); } while (0)
; #define PG8_LDA(dst, b, h) do { _Pragma("unroll") for (int m = 0; m < 4; ++m) _Pragma("unroll") for (int k = 0; k < 2; ++k) dst[m][k] = *(const PG8_LAS bf16x8*)(lds + PG8_SA(b, h) + aoff + m * 2048 + k * 1024); } while (0)
; #define PG8_LDB(dst, b, h) do { _Pragma("unroll") for (int n = 0; n < 2; ++n) _Pragma("unroll") for (int k = 0; k < 2; ++k) dst[n][k] = *(const PG8_LAS bf16x8*)(lds + PG8_SB(b, h) + boff + n * 2048 + k * 1024); } while (0)
; #define PG8_MMA(ai, bj, At, Bt) do { __builtin_amdgcn_s_setprio(1); _Pragma("unroll") for (int m = 0; m < 4; ++m) _Pragma("unroll") for (int n = 0; n < 2; ++n) _Pragma("unroll") for (int k = 0; k < 2; ++k) \
;         acc[ai][bj][m][n] = __builtin_amdgcn_mfma_f32_16x16x32_bf16(Bt[n][k], At[m][k], acc[ai][bj][m][n], 0, 0, 0); __builtin_amdgcn_s_setprio(0); } while (0)
; #define PG8_WAIT_V(n) asm volatile("s_waitcnt vmcnt(" #n ")" ::: "memory")
; #define PG8_WAIT_L(n) asm volatile("s_waitcnt lgkmcnt(" #n ")" ::: "memory")
; #define PG8_BAR __builtin_amdgcn_s_barrier()
; #define PG8_SCHED __builtin_amdgcn_sched_barrier(0)
; template <class Epi, class Sched, bool ALIGN_EPI = false, bool SP2 = false>
; __device__ __forceinline__ void gemm_phase(PG8_LAS unsigned char* lds, const Gemm g, const Sched& S, const Epi& E) {
;     ...
;         for (int t = 0; t < nt; t += 2) {
;     ...
;             PG8_LDB(B0, 1, 0); PG8_LDB(B1, 1, 1); PG8_SCHED; PG8_LDA(At, 1, 0); PG8_STAGE(PG8_SA(0, 1), a2 + hstep, voffA);
;             PG8_WAIT_V(8); PG8_WAIT_L(0); PG8_BAR; PG8_MMA(0, 0, At, B0); PG8_MMA(0, 1, At, B1); PG8_BAR; PG8_SCHED;
;             PG8_LDA(At, 1, 1); PG8_STAGE(PG8_SB(1, 0), b3, voffB); PG8_STAGE(PG8_SB(1, 1), b3 + hstep, voffB); PG8_STAGE(PG8_SA(1, 0), a3, voffA);
;             PG8_WAIT_V(8); PG8_WAIT_L(0); PG8_BAR; PG8_MMA(1, 0, At, B0); PG8_MMA(1, 1, At, B1); PG8_BAR; PG8_SCHED;
	s_setprio 0
	s_add_i32 s15, 0, 0x18000
	s_add_i32 s44, 0, 0x1c000
	ds_read_b128 v[140:143], v218 offset:32768
	ds_read_b128 v[148:151], v218 offset:33792
	ds_read_b128 v[152:155], v218 offset:34816
	ds_read_b128 v[156:159], v218 offset:35840
	ds_read_b128 v[160:163], v218 offset:49152
	ds_read_b128 v[164:167], v218 offset:50176
	ds_read_b128 v[168:171], v218 offset:51200
	ds_read_b128 v[172:175], v218 offset:52224
	s_add_u32 s10, s10, s30
	s_addc_u32 s11, s11, 0
	s_mov_b32 m0, s27
	ds_read_b128 v[176:179], v147 offset:32768
	ds_read_b128 v[180:183], v147 offset:33792
	ds_read_b128 v[184:187], v147 offset:34816
	ds_read_b128 v[188:191], v147 offset:35840
	ds_read_b128 v[192:195], v147 offset:36864
	ds_read_b128 v[196:199], v147 offset:37888
	ds_read_b128 v[200:203], v147 offset:38912
	ds_read_b128 v[204:207], v147 offset:39936
	global_load_lds_dwordx4 v130, s[10:11]
	s_mov_b32 m0, s54
	s_nop 0
	global_load_lds_dwordx4 v132, s[10:11]
	s_waitcnt vmcnt(8)
	s_waitcnt lgkmcnt(0)
	s_setprio 1
	s_barrier
	v_mfma_f32_16x16x32_bf16 v[126:129], v[140:143], v[176:179], v[126:129]
	v_mfma_f32_16x16x32_bf16 v[122:125], v[152:155], v[176:179], v[122:125]
	v_mfma_f32_16x16x32_bf16 v[110:113], v[140:143], v[184:187], v[110:113]
	v_mfma_f32_16x16x32_bf16 v[106:109], v[152:155], v[184:187], v[106:109]
	v_mfma_f32_16x16x32_bf16 v[94:97], v[140:143], v[192:195], v[94:97]
	v_mfma_f32_16x16x32_bf16 v[90:93], v[152:155], v[192:195], v[90:93]
	v_mfma_f32_16x16x32_bf16 v[78:81], v[140:143], v[200:203], v[78:81]
	v_mfma_f32_16x16x32_bf16 v[74:77], v[152:155], v[200:203], v[74:77]
	v_mfma_f32_16x16x32_bf16 v[126:129], v[148:151], v[180:183], v[126:129]
	v_mfma_f32_16x16x32_bf16 v[122:125], v[156:159], v[180:183], v[122:125]
	v_mfma_f32_16x16x32_bf16 v[110:113], v[148:151], v[188:191], v[110:113]
	v_mfma_f32_16x16x32_bf16 v[106:109], v[156:159], v[188:191], v[106:109]
	v_mfma_f32_16x16x32_bf16 v[94:97], v[148:151], v[196:199], v[94:97]
	v_mfma_f32_16x16x32_bf16 v[90:93], v[156:159], v[196:199], v[90:93]
	v_mfma_f32_16x16x32_bf16 v[78:81], v[148:151], v[204:207], v[78:81]
	v_mfma_f32_16x16x32_bf16 v[74:77], v[156:159], v[204:207], v[74:77]
	v_mfma_f32_16x16x32_bf16 v[118:121], v[160:163], v[176:179], v[118:121]
	v_mfma_f32_16x16x32_bf16 v[114:117], v[168:171], v[176:179], v[114:117]
	v_mfma_f32_16x16x32_bf16 v[102:105], v[160:163], v[184:187], v[102:105]
	v_mfma_f32_16x16x32_bf16 v[98:101], v[168:171], v[184:187], v[98:101]
	v_mfma_f32_16x16x32_bf16 v[86:89], v[160:163], v[192:195], v[86:89]
	v_mfma_f32_16x16x32_bf16 v[82:85], v[168:171], v[192:195], v[82:85]
	v_mfma_f32_16x16x32_bf16 v[70:73], v[160:163], v[200:203], v[70:73]
	v_mfma_f32_16x16x32_bf16 v[66:69], v[168:171], v[200:203], v[66:69]
	v_mfma_f32_16x16x32_bf16 v[118:121], v[164:167], v[180:183], v[118:121]
	v_mfma_f32_16x16x32_bf16 v[114:117], v[172:175], v[180:183], v[114:117]
	v_mfma_f32_16x16x32_bf16 v[102:105], v[164:167], v[188:191], v[102:105]
	v_mfma_f32_16x16x32_bf16 v[98:101], v[172:175], v[188:191], v[98:101]
	v_mfma_f32_16x16x32_bf16 v[86:89], v[164:167], v[196:199], v[86:89]
	v_mfma_f32_16x16x32_bf16 v[82:85], v[172:175], v[196:199], v[82:85]
	v_mfma_f32_16x16x32_bf16 v[70:73], v[164:167], v[204:207], v[70:73]
	v_mfma_f32_16x16x32_bf16 v[66:69], v[172:175], v[204:207], v[66:69]
	s_barrier
	s_setprio 0
	s_add_i32 s10, s15, s7
	s_mov_b32 m0, s10
	ds_read_b128 v[176:179], v147 offset:49152
	ds_read_b128 v[180:183], v147 offset:50176
	ds_read_b128 v[184:187], v147 offset:51200
	ds_read_b128 v[188:191], v147 offset:52224
	ds_read_b128 v[192:195], v147 offset:53248
	ds_read_b128 v[196:199], v147 offset:54272
	ds_read_b128 v[200:203], v147 offset:55296
	ds_read_b128 v[204:207], v147 offset:56320
	global_load_lds_dwordx4 v0, s[98:99]
	s_add_i32 m0, s10, 0x2000
	s_add_i32 s10, s44, s7
	global_load_lds_dwordx4 v134, s[98:99]
	s_mov_b32 m0, s10
	s_nop 0
	global_load_lds_dwordx4 v0, s[100:101]
	s_add_i32 m0, s10, 0x2000
	s_nop 0
	global_load_lds_dwordx4 v134, s[100:101]
	s_mov_b32 m0, s16
	s_nop 0
	global_load_lds_dwordx4 v130, vcc
	s_mov_b32 m0, s17
	s_nop 0
	global_load_lds_dwordx4 v132, vcc
	s_waitcnt vmcnt(8)
	s_waitcnt lgkmcnt(0)
	s_setprio 1
	s_barrier
	v_mfma_f32_16x16x32_bf16 v[62:65], v[140:143], v[176:179], v[62:65]
	v_mfma_f32_16x16x32_bf16 v[58:61], v[152:155], v[176:179], v[58:61]
	v_mfma_f32_16x16x32_bf16 v[46:49], v[140:143], v[184:187], v[46:49]
	v_mfma_f32_16x16x32_bf16 v[42:45], v[152:155], v[184:187], v[42:45]
	v_mfma_f32_16x16x32_bf16 v[30:33], v[140:143], v[192:195], v[30:33]
	v_mfma_f32_16x16x32_bf16 v[26:29], v[152:155], v[192:195], v[26:29]
	v_mfma_f32_16x16x32_bf16 v[14:17], v[140:143], v[200:203], v[14:17]
	v_mfma_f32_16x16x32_bf16 v[10:13], v[152:155], v[200:203], v[10:13]
	v_mfma_f32_16x16x32_bf16 v[62:65], v[148:151], v[180:183], v[62:65]
	v_mfma_f32_16x16x32_bf16 v[58:61], v[156:159], v[180:183], v[58:61]
	v_mfma_f32_16x16x32_bf16 v[46:49], v[148:151], v[188:191], v[46:49]
	v_mfma_f32_16x16x32_bf16 v[42:45], v[156:159], v[188:191], v[42:45]
	v_mfma_f32_16x16x32_bf16 v[30:33], v[148:151], v[196:199], v[30:33]
	v_mfma_f32_16x16x32_bf16 v[26:29], v[156:159], v[196:199], v[26:29]
	v_mfma_f32_16x16x32_bf16 v[14:17], v[148:151], v[204:207], v[14:17]
	v_mfma_f32_16x16x32_bf16 v[10:13], v[156:159], v[204:207], v[10:13]
	v_mfma_f32_16x16x32_bf16 v[54:57], v[160:163], v[176:179], v[54:57]
	v_mfma_f32_16x16x32_bf16 v[50:53], v[168:171], v[176:179], v[50:53]
	v_mfma_f32_16x16x32_bf16 v[38:41], v[160:163], v[184:187], v[38:41]
	v_mfma_f32_16x16x32_bf16 v[34:37], v[168:171], v[184:187], v[34:37]
	v_mfma_f32_16x16x32_bf16 v[22:25], v[160:163], v[192:195], v[22:25]
	v_mfma_f32_16x16x32_bf16 v[18:21], v[168:171], v[192:195], v[18:21]
	v_mfma_f32_16x16x32_bf16 v[6:9], v[160:163], v[200:203], v[6:9]
	v_mfma_f32_16x16x32_bf16 v[2:5], v[168:171], v[200:203], v[2:5]
	v_mfma_f32_16x16x32_bf16 v[54:57], v[164:167], v[180:183], v[54:57]
	v_mfma_f32_16x16x32_bf16 v[50:53], v[172:175], v[180:183], v[50:53]
	v_mfma_f32_16x16x32_bf16 v[38:41], v[164:167], v[188:191], v[38:41]
	v_mfma_f32_16x16x32_bf16 v[34:37], v[172:175], v[188:191], v[34:37]
	v_mfma_f32_16x16x32_bf16 v[22:25], v[164:167], v[196:199], v[22:25]
	v_mfma_f32_16x16x32_bf16 v[18:21], v[172:175], v[196:199], v[18:21]
	v_mfma_f32_16x16x32_bf16 v[6:9], v[164:167], v[204:207], v[6:9]
	v_mfma_f32_16x16x32_bf16 v[2:5], v[172:175], v[204:207], v[2:5]
	s_barrier
	s_setprio 0
	s_add_u32 s8, s8, 0x100
	s_addc_u32 s9, s9, 0
	s_add_u32 s12, s12, 0x100
	s_addc_u32 s13, s13, 0
	s_mov_b32 s10, s14

; #define PG8_STAGE(bufoff, gbase, voff) do { _Pragma("unroll") for (int _i = 0; _i < 2; ++_i) \
;         __builtin_amdgcn_global_load_lds((const unsigned*)((const char*)(gbase) + (voff)[_i]), (PG8_LAS unsigned*)(lds + (bufoff) + ldsw + _i * 8192), 16, 0, 0); } while (0)
; #define PG8_LDA(dst, b, h) do { _Pragma("unroll") for (int m = 0; m < 4; ++m) _Pragma("unroll") for (int k = 0; k < 2; ++k) dst[m][k] = *(const PG8_LAS bf16x8*)(lds + PG8_SA(b, h) + aoff + m * 2048 + k * 1024); } while (0)
; #define PG8_LDB(dst, b, h) do { _Pragma("unroll") for (int n = 0; n < 2; ++n) _Pragma("unroll") for (int k = 0; k < 2; ++k) dst[n][k] = *(const PG8_LAS bf16x8*)(lds + PG8_SB(b, h) + boff + n * 2048 + k * 1024); } while (0)
; template <class Epi, class Sched, bool ALIGN_EPI = false, bool SP2 = false>
; __device__ __forceinline__ void gemm_phase(PG8_LAS unsigned char* lds, const Gemm g, const Sched& S, const Epi& E) {
;     ...
;     f32x4 acc[2][2][4][2];
; #pragma unroll
;     for (int a = 0; a < 2; ++a)
; #pragma unroll
;         for (int b = 0; b < 2; ++b)
; #pragma unroll
;             for (int m = 0; m < 4; ++m)
; #pragma unroll
;                 for (int n = 0; n < 2; ++n) acc[a][b][m][n] = (f32x4){0.f, 0.f, 0.f, 0.f};
;     ...
;         const bool has_next = S.next(ui + 1, nxt);
;         const char* nA = has_next ? (const char*)g.A + (size_t)nxt.pm * tstep : cA; const char* nB = has_next ? (const char*)g.Bt + (size_t)nxt.pn * tstep : cB;
;         for (int t = 0; t < nt; t += 2) {
;             const bool last = (t == nt - 2);
;             const char* a1 = cA + (size_t)(t + 1) * kstep;
;             const char* a2 = last ? nA : cA + (size_t)(t + 2) * kstep; const char* b2 = last ? nB : cB + (size_t)(t + 2) * kstep;
;             const char* a3 = a2 + kstep; const char* b3 = b2 + kstep;
;             if (last && has_next) S.a_ready(nxt);
;             if constexpr (SP2) {
;             PG8_LDB(B0, 0, 0); PG8_LDB(B1, 0, 1); PG8_SCHED; PG8_LDA(At, 0, 0); PG8_STAGE(PG8_SA(1, 1), a1 + hstep, voffA);
;             PG8_WAIT_V(8); PG8_WAIT_L(0); PG8_BAR; PG8_MMA(0, 0, At, B0); PG8_MMA(0, 1, At, B1); PG8_BAR; PG8_SCHED;
;             PG8_LDA(At, 0, 1); PG8_STAGE(PG8_SB(0, 0), b2, voffB); PG8_STAGE(PG8_SB(0, 1), b2 + hstep, voffB); PG8_STAGE(PG8_SA(0, 0), a2, voffA);
;             PG8_WAIT_V(8); PG8_WAIT_L(0); PG8_BAR; PG8_MMA(1, 0, At, B0); PG8_MMA(1, 1, At, B1); PG8_BAR; PG8_SCHED;
.Lstg4_done:
	s_ashr_i32 s37, s36, 31
	s_lshl_b64 s[26:27], s[36:37], 20
	s_add_u32 s26, s18, s26
	s_addc_u32 s27, s19, s27
	s_and_b64 s[44:45], s[40:41], exec
	s_cselect_b32 s37, s27, s51
	s_cselect_b32 s43, s26, s50
	s_ashr_i32 s23, s22, 31
	s_lshl_b64 s[44:45], s[22:23], 20
	s_add_u32 s44, s96, s44
	s_addc_u32 s45, s97, s45
	s_and_b64 s[52:53], s[40:41], exec
	s_cselect_b32 s23, s45, s11
	s_cselect_b32 s56, s44, s10
	s_add_u32 s50, s50, 0x80080
	s_addc_u32 s51, s51, 0
	s_add_u32 s57, s10, 0x100
	s_addc_u32 s58, s11, 0
	s_mov_b32 s59, -2
	v_add_u32_e32 v248, 0x10000, v149
	s_add_u32 s10, s50, 0xfff80080
	s_addc_u32 s11, s51, -1
	s_add_i32 s60, 0, 0x10000
	s_cmp_eq_u32 s59, 28
	s_cselect_b32 s53, s37, s11
	s_cselect_b32 s52, s43, s10
	s_cselect_b32 s11, s23, s58
	s_cselect_b32 s10, s56, s57
	s_add_i32 s62, 0, 0x14000
	ds_read_b128 v[140:143], v248
	ds_read_b128 v[152:155], v248 offset:1024
	ds_read_b128 v[156:159], v248 offset:2048
	ds_read_b128 v[160:163], v248 offset:3072
	ds_read_b128 v[164:167], v248 offset:16384
	ds_read_b128 v[168:171], v248 offset:17408
	ds_read_b128 v[172:175], v248 offset:18432
	ds_read_b128 v[176:179], v248 offset:19456
	s_add_i32 m0, s5, 0xc000
	ds_read_b128 v[180:183], v151
	ds_read_b128 v[184:187], v151 offset:1024
	ds_read_b128 v[188:191], v151 offset:2048
	ds_read_b128 v[192:195], v151 offset:3072
	ds_read_b128 v[196:199], v151 offset:4096
	ds_read_b128 v[200:203], v151 offset:5120
	ds_read_b128 v[204:207], v151 offset:6144
	ds_read_b128 v[208:211], v151 offset:7168
	global_load_lds_dwordx4 v136, s[50:51]
	s_add_i32 m0, s5, 0xe000
	s_nop 0
	global_load_lds_dwordx4 v138, s[50:51]
	s_waitcnt vmcnt(8)
	s_waitcnt lgkmcnt(0)
	s_setprio 1
	s_barrier
	v_mfma_f32_16x16x32_bf16 v[126:129], v[140:143], v[180:183], 0
	v_mfma_f32_16x16x32_bf16 v[122:125], v[156:159], v[180:183], 0
	v_mfma_f32_16x16x32_bf16 v[110:113], v[140:143], v[188:191], 0
	v_mfma_f32_16x16x32_bf16 v[106:109], v[156:159], v[188:191], 0
	v_mfma_f32_16x16x32_bf16 v[94:97], v[140:143], v[196:199], 0
	v_mfma_f32_16x16x32_bf16 v[90:93], v[156:159], v[196:199], 0
	v_mfma_f32_16x16x32_bf16 v[78:81], v[140:143], v[204:207], 0
	v_mfma_f32_16x16x32_bf16 v[74:77], v[156:159], v[204:207], 0
	v_mfma_f32_16x16x32_bf16 v[126:129], v[152:155], v[184:187], v[126:129]
	v_mfma_f32_16x16x32_bf16 v[122:125], v[160:163], v[184:187], v[122:125]
	v_mfma_f32_16x16x32_bf16 v[110:113], v[152:155], v[192:195], v[110:113]
	v_mfma_f32_16x16x32_bf16 v[106:109], v[160:163], v[192:195], v[106:109]
	v_mfma_f32_16x16x32_bf16 v[94:97], v[152:155], v[200:203], v[94:97]
	v_mfma_f32_16x16x32_bf16 v[90:93], v[160:163], v[200:203], v[90:93]
	v_mfma_f32_16x16x32_bf16 v[78:81], v[152:155], v[208:211], v[78:81]
	v_mfma_f32_16x16x32_bf16 v[74:77], v[160:163], v[208:211], v[74:77]
	v_mfma_f32_16x16x32_bf16 v[118:121], v[164:167], v[180:183], 0
	v_mfma_f32_16x16x32_bf16 v[114:117], v[172:175], v[180:183], 0
	v_mfma_f32_16x16x32_bf16 v[102:105], v[164:167], v[188:191], 0
	v_mfma_f32_16x16x32_bf16 v[98:101], v[172:175], v[188:191], 0
	v_mfma_f32_16x16x32_bf16 v[86:89], v[164:167], v[196:199], 0
	v_mfma_f32_16x16x32_bf16 v[82:85], v[172:175], v[196:199], 0
	v_mfma_f32_16x16x32_bf16 v[70:73], v[164:167], v[204:207], 0
	v_mfma_f32_16x16x32_bf16 v[66:69], v[172:175], v[204:207], 0
	v_mfma_f32_16x16x32_bf16 v[118:121], v[168:171], v[184:187], v[118:121]
	v_mfma_f32_16x16x32_bf16 v[114:117], v[176:179], v[184:187], v[114:117]
	v_mfma_f32_16x16x32_bf16 v[102:105], v[168:171], v[192:195], v[102:105]
	v_mfma_f32_16x16x32_bf16 v[98:101], v[176:179], v[192:195], v[98:101]
	v_mfma_f32_16x16x32_bf16 v[86:89], v[168:171], v[200:203], v[86:89]
	v_mfma_f32_16x16x32_bf16 v[82:85], v[176:179], v[200:203], v[82:85]
	v_mfma_f32_16x16x32_bf16 v[70:73], v[168:171], v[208:211], v[70:73]
	v_mfma_f32_16x16x32_bf16 v[66:69], v[176:179], v[208:211], v[66:69]
	s_barrier
	s_setprio 0
	s_add_i32 s60, s60, s4
	s_add_u32 s100, s10, 0x80
	s_addc_u32 s101, s11, 0
	s_mov_b32 m0, s60
	ds_read_b128 v[180:183], v151 offset:16384
	ds_read_b128 v[184:187], v151 offset:17408
	ds_read_b128 v[188:191], v151 offset:18432
	ds_read_b128 v[192:195], v151 offset:19456
	ds_read_b128 v[196:199], v151 offset:20480
	ds_read_b128 v[200:203], v151 offset:21504
	ds_read_b128 v[204:207], v151 offset:22528
	ds_read_b128 v[208:211], v151 offset:23552
	global_load_lds_dwordx4 v0, s[10:11]
	s_add_i32 m0, s60, 0x2000
	s_add_u32 s60, s10, 0x80000
	s_addc_u32 s61, s11, 0
	s_add_i32 s62, s62, s4
	global_load_lds_dwordx4 v134, s[10:11]
	s_mov_b32 m0, s62
	s_add_u32 s98, s52, 0x80
	s_addc_u32 s99, s53, 0
	global_load_lds_dwordx4 v0, s[60:61]
	s_add_i32 m0, s62, 0x2000
	s_nop 0
	global_load_lds_dwordx4 v134, s[60:61]
	s_mov_b32 m0, s5
	s_nop 0
	global_load_lds_dwordx4 v130, s[52:53]
	s_mov_b32 m0, s6
	s_nop 0
	global_load_lds_dwordx4 v132, s[52:53]
	s_waitcnt vmcnt(8)
	s_waitcnt lgkmcnt(0)
	s_setprio 1
	s_barrier
; #define PG8_STAGE(bufoff, gbase, voff) do { _Pragma("unroll") for (int _i = 0; _i < 2; ++_i) \
;         __builtin_amdgcn_global_load_lds((const unsigned*)((const char*)(gbase) + (voff)[_i]), (PG8_LAS unsigned*)(lds + (bufoff) + ldsw + _i * 8192), 16, 0, 0); } while (0)
; #define PG8_LDA(dst, b, h) do { _Pragma("unroll") for (int m = 0; m < 4; ++m) _Pragma("unroll") for (int k = 0; k < 2; ++k) dst[m][k] = *(const PG8_LAS bf16x8*)(lds + PG8_SA(b, h) + aoff + m * 2048 + k * 1024); } while (0)
; #define PG8_LDB(dst, b, h) do { _Pragma("unroll") for (int n = 0; n < 2; ++n) _Pragma("unroll") for (int k = 0; k < 2; ++k) dst[n][k] = *(const PG8_LAS bf16x8*)(lds + PG8_SB(b, h) + boff + n * 2048 + k * 1024); } while (0)
; #define PG8_MMA(ai, bj, At, Bt) do { __builtin_amdgcn_s_setprio(1); _Pragma("unroll") for (int m = 0; m < 4; ++m) _Pragma("unroll") for (int n = 0; n < 2; ++n) _Pragma("unroll") for (int k = 0; k < 2; ++k) \
;         acc[ai][bj][m][n] = __builtin_amdgcn_mfma_f32_16x16x32_bf16(Bt[n][k], At[m][k], acc[ai][bj][m][n], 0, 0, 0); __builtin_amdgcn_s_setprio(0); } while (0)
; #define PG8_WAIT_V(n) asm volatile("s_waitcnt vmcnt(" #n ")" ::: "memory")
; #define PG8_WAIT_L(n) asm volatile("s_waitcnt lgkmcnt(" #n ")" ::: "memory")
; #define PG8_BAR __builtin_amdgcn_s_barrier()
; #define PG8_SCHED __builtin_amdgcn_sched_barrier(0)
; template <class Epi, class Sched, bool ALIGN_EPI = false, bool SP2 = false>
; __device__ __forceinline__ void gemm_phase(PG8_LAS unsigned char* lds, const Gemm g, const Sched& S, const Epi& E) {
;     ...
;             PG8_WAIT_V(8); PG8_WAIT_L(0); PG8_BAR; PG8_MMA(1, 0, At, B0); PG8_MMA(1, 1, At, B1); PG8_BAR; PG8_SCHED;
;             PG8_LDB(B0, 1, 0); PG8_LDB(B1, 1, 1); PG8_SCHED; PG8_LDA(At, 1, 0); PG8_STAGE(PG8_SA(0, 1), a2 + hstep, voffA);
;             PG8_WAIT_V(8); PG8_WAIT_L(0); PG8_BAR; PG8_MMA(0, 0, At, B0); PG8_MMA(0, 1, At, B1); PG8_BAR; PG8_SCHED;
	v_mfma_f32_16x16x32_bf16 v[62:65], v[140:143], v[180:183], 0
	v_mfma_f32_16x16x32_bf16 v[58:61], v[156:159], v[180:183], 0
	v_mfma_f32_16x16x32_bf16 v[46:49], v[140:143], v[188:191], 0
	v_mfma_f32_16x16x32_bf16 v[42:45], v[156:159], v[188:191], 0
	v_mfma_f32_16x16x32_bf16 v[30:33], v[140:143], v[196:199], 0
	v_mfma_f32_16x16x32_bf16 v[26:29], v[156:159], v[196:199], 0
	v_mfma_f32_16x16x32_bf16 v[14:17], v[140:143], v[204:207], 0
	v_mfma_f32_16x16x32_bf16 v[10:13], v[156:159], v[204:207], 0
	v_mfma_f32_16x16x32_bf16 v[62:65], v[152:155], v[184:187], v[62:65]
	v_mfma_f32_16x16x32_bf16 v[58:61], v[160:163], v[184:187], v[58:61]
	v_mfma_f32_16x16x32_bf16 v[46:49], v[152:155], v[192:195], v[46:49]
	v_mfma_f32_16x16x32_bf16 v[42:45], v[160:163], v[192:195], v[42:45]
	v_mfma_f32_16x16x32_bf16 v[30:33], v[152:155], v[200:203], v[30:33]
	v_mfma_f32_16x16x32_bf16 v[26:29], v[160:163], v[200:203], v[26:29]
	v_mfma_f32_16x16x32_bf16 v[14:17], v[152:155], v[208:211], v[14:17]
	v_mfma_f32_16x16x32_bf16 v[10:13], v[160:163], v[208:211], v[10:13]
	v_mfma_f32_16x16x32_bf16 v[54:57], v[164:167], v[180:183], 0
	v_mfma_f32_16x16x32_bf16 v[50:53], v[172:175], v[180:183], 0
	v_mfma_f32_16x16x32_bf16 v[38:41], v[164:167], v[188:191], 0
	v_mfma_f32_16x16x32_bf16 v[34:37], v[172:175], v[188:191], 0
	v_mfma_f32_16x16x32_bf16 v[22:25], v[164:167], v[196:199], 0
	v_mfma_f32_16x16x32_bf16 v[18:21], v[172:175], v[196:199], 0
	v_mfma_f32_16x16x32_bf16 v[6:9], v[164:167], v[204:207], 0
	v_mfma_f32_16x16x32_bf16 v[2:5], v[172:175], v[204:207], 0
	v_mfma_f32_16x16x32_bf16 v[54:57], v[168:171], v[184:187], v[54:57]
	v_mfma_f32_16x16x32_bf16 v[50:53], v[176:179], v[184:187], v[50:53]
	v_mfma_f32_16x16x32_bf16 v[38:41], v[168:171], v[192:195], v[38:41]
	v_mfma_f32_16x16x32_bf16 v[34:37], v[176:179], v[192:195], v[34:37]
	v_mfma_f32_16x16x32_bf16 v[22:25], v[168:171], v[200:203], v[22:25]
	v_mfma_f32_16x16x32_bf16 v[18:21], v[176:179], v[200:203], v[18:21]
	v_mfma_f32_16x16x32_bf16 v[6:9], v[168:171], v[208:211], v[6:9]
	v_mfma_f32_16x16x32_bf16 v[2:5], v[176:179], v[208:211], v[2:5]
	s_barrier
	s_setprio 0
	s_add_i32 s60, 0, 0x18000
	s_add_i32 s61, 0, 0x1c000
	ds_read_b128 v[140:143], v248 offset:32768
	ds_read_b128 v[152:155], v248 offset:33792
	ds_read_b128 v[156:159], v248 offset:34816
	ds_read_b128 v[160:163], v248 offset:35840
	ds_read_b128 v[164:167], v248 offset:49152
	ds_read_b128 v[168:171], v248 offset:50176
	ds_read_b128 v[172:175], v248 offset:51200
	ds_read_b128 v[176:179], v248 offset:52224
	s_add_u32 s52, s52, 0x80000
	s_addc_u32 s53, s53, 0
	s_mov_b32 m0, s7
	ds_read_b128 v[180:183], v151 offset:32768
	ds_read_b128 v[184:187], v151 offset:33792
	ds_read_b128 v[188:191], v151 offset:34816
	ds_read_b128 v[192:195], v151 offset:35840
	ds_read_b128 v[196:199], v151 offset:36864
	ds_read_b128 v[200:203], v151 offset:37888
	ds_read_b128 v[204:207], v151 offset:38912
	ds_read_b128 v[208:211], v151 offset:39936
	global_load_lds_dwordx4 v130, s[52:53]
	s_mov_b32 m0, s17
	s_nop 0
	global_load_lds_dwordx4 v132, s[52:53]
	s_waitcnt vmcnt(8)
	s_waitcnt lgkmcnt(0)
	s_setprio 1
	s_barrier
	v_mfma_f32_16x16x32_bf16 v[126:129], v[140:143], v[180:183], v[126:129]
	v_mfma_f32_16x16x32_bf16 v[122:125], v[156:159], v[180:183], v[122:125]
	v_mfma_f32_16x16x32_bf16 v[110:113], v[140:143], v[188:191], v[110:113]
	v_mfma_f32_16x16x32_bf16 v[106:109], v[156:159], v[188:191], v[106:109]
	v_mfma_f32_16x16x32_bf16 v[94:97], v[140:143], v[196:199], v[94:97]
	v_mfma_f32_16x16x32_bf16 v[90:93], v[156:159], v[196:199], v[90:93]
	v_mfma_f32_16x16x32_bf16 v[78:81], v[140:143], v[204:207], v[78:81]
	v_mfma_f32_16x16x32_bf16 v[74:77], v[156:159], v[204:207], v[74:77]
	v_mfma_f32_16x16x32_bf16 v[126:129], v[152:155], v[184:187], v[126:129]
	v_mfma_f32_16x16x32_bf16 v[122:125], v[160:163], v[184:187], v[122:125]
	v_mfma_f32_16x16x32_bf16 v[110:113], v[152:155], v[192:195], v[110:113]
	v_mfma_f32_16x16x32_bf16 v[106:109], v[160:163], v[192:195], v[106:109]
	v_mfma_f32_16x16x32_bf16 v[94:97], v[152:155], v[200:203], v[94:97]
	v_mfma_f32_16x16x32_bf16 v[90:93], v[160:163], v[200:203], v[90:93]
	v_mfma_f32_16x16x32_bf16 v[78:81], v[152:155], v[208:211], v[78:81]
	v_mfma_f32_16x16x32_bf16 v[74:77], v[160:163], v[208:211], v[74:77]
	v_mfma_f32_16x16x32_bf16 v[118:121], v[164:167], v[180:183], v[118:121]
	v_mfma_f32_16x16x32_bf16 v[114:117], v[172:175], v[180:183], v[114:117]
	v_mfma_f32_16x16x32_bf16 v[102:105], v[164:167], v[188:191], v[102:105]
	v_mfma_f32_16x16x32_bf16 v[98:101], v[172:175], v[188:191], v[98:101]
	v_mfma_f32_16x16x32_bf16 v[86:89], v[164:167], v[196:199], v[86:89]
	v_mfma_f32_16x16x32_bf16 v[82:85], v[172:175], v[196:199], v[82:85]
	v_mfma_f32_16x16x32_bf16 v[70:73], v[164:167], v[204:207], v[70:73]
	v_mfma_f32_16x16x32_bf16 v[66:69], v[172:175], v[204:207], v[66:69]
	v_mfma_f32_16x16x32_bf16 v[118:121], v[168:171], v[184:187], v[118:121]
	v_mfma_f32_16x16x32_bf16 v[114:117], v[176:179], v[184:187], v[114:117]
	v_mfma_f32_16x16x32_bf16 v[102:105], v[168:171], v[192:195], v[102:105]
	v_mfma_f32_16x16x32_bf16 v[98:101], v[176:179], v[192:195], v[98:101]
	v_mfma_f32_16x16x32_bf16 v[86:89], v[168:171], v[200:203], v[86:89]
	v_mfma_f32_16x16x32_bf16 v[82:85], v[176:179], v[200:203], v[82:85]
	v_mfma_f32_16x16x32_bf16 v[70:73], v[168:171], v[208:211], v[70:73]
	v_mfma_f32_16x16x32_bf16 v[66:69], v[176:179], v[208:211], v[66:69]
	s_barrier
; #define PG8_STAGE(bufoff, gbase, voff) do { _Pragma("unroll") for (int _i = 0; _i < 2; ++_i) \
;         __builtin_amdgcn_global_load_lds((const unsigned*)((const char*)(gbase) + (voff)[_i]), (PG8_LAS unsigned*)(lds + (bufoff) + ldsw + _i * 8192), 16, 0, 0); } while (0)
; #define PG8_LDA(dst, b, h) do { _Pragma("unroll") for (int m = 0; m < 4; ++m) _Pragma("unroll") for (int k = 0; k < 2; ++k) dst[m][k] = *(const PG8_LAS bf16x8*)(lds + PG8_SA(b, h) + aoff + m * 2048 + k * 1024); } while (0)
; #define PG8_MMA(ai, bj, At, Bt) do { __builtin_amdgcn_s_setprio(1); _Pragma("unroll") for (int m = 0; m < 4; ++m) _Pragma("unroll") for (int n = 0; n < 2; ++n) _Pragma("unroll") for (int k = 0; k < 2; ++k) \
;         acc[ai][bj][m][n] = __builtin_amdgcn_mfma_f32_16x16x32_bf16(Bt[n][k], At[m][k], acc[ai][bj][m][n], 0, 0, 0); __builtin_amdgcn_s_setprio(0); } while (0)
; #define PG8_WAIT_V(n) asm volatile("s_waitcnt vmcnt(" #n ")" ::: "memory")
; #define PG8_WAIT_L(n) asm volatile("s_waitcnt lgkmcnt(" #n ")" ::: "memory")
; #define PG8_BAR __builtin_amdgcn_s_barrier()
; #define PG8_SCHED __builtin_amdgcn_sched_barrier(0)
; template <class Epi, class Sched, bool ALIGN_EPI = false, bool SP2 = false>
; __device__ __forceinline__ void gemm_phase(PG8_LAS unsigned char* lds, const Gemm g, const Sched& S, const Epi& E) {
;     ...
;         for (int t = 0; t < nt; t += 2) {
;     ...
;             PG8_LDA(At, 1, 1); PG8_STAGE(PG8_SB(1, 0), b3, voffB); PG8_STAGE(PG8_SB(1, 1), b3 + hstep, voffB); PG8_STAGE(PG8_SA(1, 0), a3, voffA);
;             PG8_WAIT_V(8); PG8_WAIT_L(0); PG8_BAR; PG8_MMA(1, 0, At, B0); PG8_MMA(1, 1, At, B1); PG8_BAR; PG8_SCHED;
	s_setprio 0
	s_add_i32 s52, s60, s4
	s_mov_b32 m0, s52
	ds_read_b128 v[180:183], v151 offset:49152
	ds_read_b128 v[184:187], v151 offset:50176
	ds_read_b128 v[188:191], v151 offset:51200
	ds_read_b128 v[192:195], v151 offset:52224
	ds_read_b128 v[196:199], v151 offset:53248
	ds_read_b128 v[200:203], v151 offset:54272
	ds_read_b128 v[204:207], v151 offset:55296
	ds_read_b128 v[208:211], v151 offset:56320
	global_load_lds_dwordx4 v0, s[100:101]
	s_add_i32 m0, s52, 0x2000
	s_add_i32 s52, s61, s4
	global_load_lds_dwordx4 v134, s[100:101]
	s_add_u32 s10, s10, 0x80080
	s_addc_u32 s11, s11, 0
	s_mov_b32 m0, s52
	s_nop 0
	global_load_lds_dwordx4 v0, s[10:11]
	s_add_i32 m0, s52, 0x2000
	s_nop 0
	global_load_lds_dwordx4 v134, s[10:11]
	s_mov_b32 m0, s30
	s_nop 0
	global_load_lds_dwordx4 v130, s[98:99]
	s_mov_b32 m0, s47
	s_nop 0
	global_load_lds_dwordx4 v132, s[98:99]
	s_waitcnt vmcnt(8)
	s_waitcnt lgkmcnt(0)
	s_setprio 1
	s_barrier
	v_mfma_f32_16x16x32_bf16 v[62:65], v[140:143], v[180:183], v[62:65]
	v_mfma_f32_16x16x32_bf16 v[58:61], v[156:159], v[180:183], v[58:61]
	v_mfma_f32_16x16x32_bf16 v[46:49], v[140:143], v[188:191], v[46:49]
	v_mfma_f32_16x16x32_bf16 v[42:45], v[156:159], v[188:191], v[42:45]
	v_mfma_f32_16x16x32_bf16 v[30:33], v[140:143], v[196:199], v[30:33]
	v_mfma_f32_16x16x32_bf16 v[26:29], v[156:159], v[196:199], v[26:29]
	v_mfma_f32_16x16x32_bf16 v[14:17], v[140:143], v[204:207], v[14:17]
	v_mfma_f32_16x16x32_bf16 v[10:13], v[156:159], v[204:207], v[10:13]
	v_mfma_f32_16x16x32_bf16 v[62:65], v[152:155], v[184:187], v[62:65]
	v_mfma_f32_16x16x32_bf16 v[58:61], v[160:163], v[184:187], v[58:61]
	v_mfma_f32_16x16x32_bf16 v[46:49], v[152:155], v[192:195], v[46:49]
	v_mfma_f32_16x16x32_bf16 v[42:45], v[160:163], v[192:195], v[42:45]
	v_mfma_f32_16x16x32_bf16 v[30:33], v[152:155], v[200:203], v[30:33]
	v_mfma_f32_16x16x32_bf16 v[26:29], v[160:163], v[200:203], v[26:29]
	v_mfma_f32_16x16x32_bf16 v[14:17], v[152:155], v[208:211], v[14:17]
	v_mfma_f32_16x16x32_bf16 v[10:13], v[160:163], v[208:211], v[10:13]
	v_mfma_f32_16x16x32_bf16 v[54:57], v[164:167], v[180:183], v[54:57]
	v_mfma_f32_16x16x32_bf16 v[50:53], v[172:175], v[180:183], v[50:53]
	v_mfma_f32_16x16x32_bf16 v[38:41], v[164:167], v[188:191], v[38:41]
	v_mfma_f32_16x16x32_bf16 v[34:37], v[172:175], v[188:191], v[34:37]
	v_mfma_f32_16x16x32_bf16 v[22:25], v[164:167], v[196:199], v[22:25]
	v_mfma_f32_16x16x32_bf16 v[18:21], v[172:175], v[196:199], v[18:21]
	v_mfma_f32_16x16x32_bf16 v[6:9], v[164:167], v[204:207], v[6:9]
	v_mfma_f32_16x16x32_bf16 v[2:5], v[172:175], v[204:207], v[2:5]
	v_mfma_f32_16x16x32_bf16 v[54:57], v[168:171], v[184:187], v[54:57]
	v_mfma_f32_16x16x32_bf16 v[50:53], v[176:179], v[184:187], v[50:53]
	v_mfma_f32_16x16x32_bf16 v[38:41], v[168:171], v[192:195], v[38:41]
	v_mfma_f32_16x16x32_bf16 v[34:37], v[176:179], v[192:195], v[34:37]
	v_mfma_f32_16x16x32_bf16 v[22:25], v[168:171], v[200:203], v[22:25]
	v_mfma_f32_16x16x32_bf16 v[18:21], v[176:179], v[200:203], v[18:21]
	v_mfma_f32_16x16x32_bf16 v[6:9], v[168:171], v[208:211], v[6:9]
	v_mfma_f32_16x16x32_bf16 v[2:5], v[176:179], v[208:211], v[2:5]
	s_barrier
	s_setprio 0
	s_add_i32 s59, s59, 2
	s_add_u32 s50, s50, 0x100
	s_addc_u32 s51, s51, 0
	s_add_u32 s57, s57, 0x100
	s_addc_u32 s58, s58, 0
